# h3 epilogue: norm_g loaded once per item; slot loop: CUs with odd physical CU id run in-proj before PEER retrieval (opposite order on even CUs)
# speedup vs baseline: 1.0801x; 1.0156x over previous
; #define LND asm volatile("" : "+s"(l), "+s"(pass))
; #define GSYNC xcd_barrier(bar, xcc, nloc, nx)
; __global__ void __launch_bounds__(256, 2) fwd_megakernel(Params P) {
;     ...
;     for (int it = 0; it < 3; ++it) {
; #pragma unroll 1
;       for (int step = 0; step < 2; ++step) {
;         int pass;
;         if ((step ^ role) == 0) {
;           if (it < 2) { pass = __builtin_amdgcn_readfirstlane(it); LND; phase_inproj(P, l, pass, smem); }
;         } else {
;           if (it > 0) { pass = __builtin_amdgcn_readfirstlane(it - 1); LND; phase11(P, l, pass, smem); }
;         }
;       }
;       if (!(l == 1 && it == 2)) GSYNC;
.LBB0_123:
	s_cmp_lg_u32 s51, 0
	s_cselect_b64 s[26:27], -1, 0
	s_cmp_eq_u32 s51, 2
	s_cselect_b64 s[4:5], -1, 0
	v_writelane_b32 v252, s4, 34
	s_cmp_lg_u32 s51, 2
	s_cselect_b64 s[6:7], -1, 0
	v_writelane_b32 v252, s5, 35
	v_writelane_b32 v252, s51, 36
	s_mov_b64 s[72:73], -1
	s_mov_b32 s2, s0
	v_writelane_b32 v252, s6, 37
	s_nop 1
	v_writelane_b32 v252, s7, 38
	s_mov_b64 s[40:41], -1
	s_getreg_b32 vcc_lo, hwreg(HW_REG_HW_ID)
	s_nop 1
	s_bitcmp1_b32 vcc_lo, 8
	s_cbranch_scc1 .LBB0_277
	s_branch .LBB0_125
.Lsplit_latch:
	s_getreg_b32 vcc_lo, hwreg(HW_REG_HW_ID)
	s_nop 1
	s_bitcmp1_b32 vcc_lo, 8
	s_cbranch_scc0 .LBB0_124
	s_waitcnt vmcnt(0) lgkmcnt(0)
	s_barrier
	v_readlane_b32 s51, v252, 36
	s_mov_b32 s2, s0
	s_nop 1
	s_cmp_lg_u32 s51, 0
	s_cselect_b64 s[26:27], -1, 0
	s_branch .LBB0_125

; DEVI float b2f(bfu b) { return __uint_as_float(((unsigned)b) << 16); }
; DEVI float siluf_(float x) { return x / (1.f + __expf(-x)); }
; DEVI void h3_item(const Params& P, int l, int ck, int h, char* smem, int tid) {
;   const ChunkInfo ci = chunkinfo(ck);
;   const int lane = tid & 63, w = tid >> 6, fr = lane & 15, fq = lane >> 4;
;   bfu* QT = (bfu*)smem;
;   bfu* KT = QT + 64 * 136;
;   bfu* AT = KT + 64 * 136;
;   bfu* BS = AT + 64 * 72;
;   float* bmid = (float*)(BS + 128 * 72);
;   const int d = tid & 127, hf = tid >> 7, L = ci.L, Lh = L >> 1;
;   const float lb = ((const float*)(P.ws + O_LBS))[l * 1024 + h * 128 + d];
;   const bfu* Z = (const bfu*)(P.ws + O_Z);
;   const bfu* zqb = Z + (long)ci.lt0 * NCOL + 5 * 1024 + h * 128;
;   __syncthreads();
;   {
;     uint4 vq[4], vf[4], vi[4];
; #pragma unroll
;     for (int q = 0; q < 4; ++q) {
;       const int idx = tid + 256 * q;
;       const int sr = (idx & 15) | (((idx >> 8) & 3) << 4), c16 = ((idx >> 4) & 3) | (((idx >> 6) & 3) << 2);
;       if (sr < L) {
;         const bfu* rp = zqb + (long)sr * NCOL + c16 * 8;
;         vq[q] = *reinterpret_cast<const uint4*>(rp);
;         vf[q] = *reinterpret_cast<const uint4*>(rp + 1024);
;         vi[q] = *reinterpret_cast<const uint4*>(rp + 2048);
;       } else { vq[q] = make_uint4(0, 0, 0, 0); vf[q] = vq[q]; vi[q] = vq[q]; }
;     }
;     ...
;   const float* ng = P.in[17] + l * 128;
;   bfu* UC = (bfu*)(P.ws + O_UC);
; #pragma unroll
;   for (int n = 0; n < 8; ++n)
; #pragma unroll
;     for (int j = 0; j < 4; ++j) {
;       int t = 16 * w + fq * 4 + j, e = n * 16 + fr;
;       if (t < L) {
;         float g = b2f(QT[t * 136 + e]);
;         UC[(long)(ci.lt0 + t) * 1024 + h * 128 + e] = f2b(o[n][j] * rinv[j] * ng[e] * siluf_(g));
.LBB0_538:
	global_load_dword v219, v[118:119], off
	global_load_dword v220, v[118:119], off offset:64
	global_load_dword v221, v[118:119], off offset:128
	global_load_dword v222, v[118:119], off offset:192
	global_load_dword v223, v[118:119], off offset:256
	global_load_dword v224, v[118:119], off offset:320
	global_load_dword v225, v[118:119], off offset:384
	global_load_dword v226, v[118:119], off offset:448
	s_and_b32 s54, s2, 7
	s_lshl_b32 s24, s54, 7
	v_or_b32_e32 v0, s24, v170
	v_readlane_b32 s4, v252, 8
	v_ashrrev_i32_e32 v1, 31, v0
	v_readlane_b32 s5, v252, 9
	s_mul_i32 s56, s50, 0x6000
	s_mul_hi_i32 s55, s50, 0x6000
	v_lshl_add_u64 v[0:1], v[0:1], 2, s[4:5]
	global_load_dword v58, v[0:1], off
	s_add_u32 s56, s30, s56
	s_addc_u32 s55, s31, s55
	s_lshl_b32 s57, s54, 8
	s_add_u32 s56, s56, s57
	s_addc_u32 s55, s55, 0
	s_add_u32 s84, s56, 0x8584800
	s_addc_u32 s85, s55, 0
	v_lshlrev_b32_e32 v88, 1, v100
	v_lshl_add_u64 v[56:57], s[84:85], 0, v[88:89]
	v_cmp_gt_u32_e64 s[74:75], s51, v171
	v_mov_b32_e32 v6, 0
	v_mov_b32_e32 v0, 0
	v_lshlrev_b32_e32 v48, 1, v102
	v_mov_b32_e32 v8, 0
	v_mov_b32_e32 v9, 0
	v_mov_b32_e32 v10, 0
	v_mov_b32_e32 v11, 0
	v_mov_b32_e32 v12, 0
	v_mov_b32_e32 v13, 0
	v_mov_b32_e32 v14, 0
	v_mov_b32_e32 v15, 0
	v_mov_b32_e32 v7, 0
	v_mov_b32_e32 v4, 0
	v_mov_b32_e32 v5, 0
	s_waitcnt vmcnt(63) expcnt(7) lgkmcnt(15)
	s_barrier
	s_and_saveexec_b64 s[76:77], s[74:75]
	s_cbranch_execz .LBB0_540
	v_mov_b32_e32 v49, v89
	v_lshl_add_u64 v[2:3], v[56:57], 0, v[48:49]
	global_load_dwordx4 v[8:11], v[2:3], off
	global_load_dwordx4 v[12:15], v[2:3], off offset:2048
	v_add_co_u32_e32 v2, vcc, 0x1000, v2
	s_nop 1
	v_addc_co_u32_e32 v3, vcc, 0, v3, vcc
	global_load_dwordx4 v[4:7], v[2:3], off

; DEVI float b2f(bfu b) { return __uint_as_float(((unsigned)b) << 16); }
; DEVI float siluf_(float x) { return x / (1.f + __expf(-x)); }
; DEVI void h3_item(const Params& P, int l, int ck, int h, char* smem, int tid) {
;     ...
;     __syncthreads();
; #pragma unroll
;     for (int kk = 0; kk < 2; ++kk) {
; #pragma unroll
;       for (int n = 0; n < 8; ++n) {
;         bf16x8 b = *reinterpret_cast<const bf16x8*>(BS + (n * 16 + fr) * 72 + kk * 32 + fq * 8);
;         o[n] = __builtin_amdgcn_mfma_f32_16x16x32_bf16(aq[sl * 2 + kk], b, o[n], 0, 0, 0);
;       }
;     }
;   }
;   float rinv[4];
; #pragma unroll
;   for (int j = 0; j < 4; ++j) {
;     float ss = 0.f;
; #pragma unroll
;     for (int n = 0; n < 8; ++n) ss += o[n][j] * o[n][j];
;     ss += __shfl_xor(ss, 1); ss += __shfl_xor(ss, 2); ss += __shfl_xor(ss, 4); ss += __shfl_xor(ss, 8);
;     rinv[j] = rsqrtf(ss * (1.f / 128.f) + 1e-6f);
;   }
;   const float* ng = P.in[17] + l * 128;
;   bfu* UC = (bfu*)(P.ws + O_UC);
; #pragma unroll
;   for (int n = 0; n < 8; ++n)
; #pragma unroll
;     for (int j = 0; j < 4; ++j) {
;       int t = 16 * w + fq * 4 + j, e = n * 16 + fr;
;       if (t < L) {
;         float g = b2f(QT[t * 136 + e]);
;         UC[(long)(ci.lt0 + t) * 1024 + h * 128 + e] = f2b(o[n][j] * rinv[j] * ng[e] * siluf_(g));
;       }
;     }
.LBB0_580:
	s_waitcnt vmcnt(0)
	s_waitcnt lgkmcnt(0)
	s_barrier
	ds_read_b128 v[40:43], v217 offset:44032
	s_brev_b32 s4, 60
	s_waitcnt lgkmcnt(0)
	v_mfma_f32_16x16x32_bf16 v[12:15], v[4:7], v[40:43], v[12:15]
	ds_read_b128 v[40:43], v217 offset:46336
	s_lshl_b32 s24, s24, 1
	v_cmp_gt_i32_e64 s[74:75], s51, v201
	s_waitcnt lgkmcnt(0)
	v_mfma_f32_16x16x32_bf16 v[16:19], v[4:7], v[40:43], v[16:19]
	ds_read_b128 v[40:43], v217 offset:48640
	s_waitcnt lgkmcnt(0)
	v_mfma_f32_16x16x32_bf16 v[20:23], v[4:7], v[40:43], v[20:23]
	ds_read_b128 v[40:43], v217 offset:50944
	s_waitcnt lgkmcnt(0)
	v_mfma_f32_16x16x32_bf16 v[40:43], v[4:7], v[40:43], v[24:27]
	s_nop 2
	ds_read_b128 v[24:27], v217 offset:53248
	s_waitcnt lgkmcnt(0)
	v_mfma_f32_16x16x32_bf16 v[44:47], v[4:7], v[24:27], v[28:31]
	ds_read_b128 v[24:27], v217 offset:55552
	s_waitcnt lgkmcnt(0)
	v_mfma_f32_16x16x32_bf16 v[32:35], v[4:7], v[24:27], v[32:35]
	ds_read_b128 v[24:27], v217 offset:57856
	s_waitcnt lgkmcnt(0)
	v_mfma_f32_16x16x32_bf16 v[36:39], v[4:7], v[24:27], v[36:39]
	ds_read_b128 v[24:27], v217 offset:60160
	s_waitcnt lgkmcnt(0)
	v_mfma_f32_16x16x32_bf16 v[48:51], v[4:7], v[24:27], v[8:11]
	ds_read_b128 v[4:7], v217 offset:44096
	s_waitcnt lgkmcnt(0)
	v_mfma_f32_16x16x32_bf16 v[28:31], v[0:3], v[4:7], v[12:15]
	ds_read_b128 v[4:7], v217 offset:46400
	s_waitcnt lgkmcnt(0)
	v_mfma_f32_16x16x32_bf16 v[24:27], v[0:3], v[4:7], v[16:19]
	ds_read_b128 v[4:7], v217 offset:48704
	s_waitcnt lgkmcnt(0)
	v_mfma_f32_16x16x32_bf16 v[20:23], v[0:3], v[4:7], v[20:23]
	ds_read_b128 v[4:7], v217 offset:51008
	s_waitcnt lgkmcnt(0)
	v_mfma_f32_16x16x32_bf16 v[16:19], v[0:3], v[4:7], v[40:43]
	ds_read_b128 v[4:7], v217 offset:53312
	s_nop 1
	v_pk_mul_f32 v[42:43], v[24:25], v[24:25]
	v_pk_mul_f32 v[40:41], v[26:27], v[26:27]
	s_waitcnt lgkmcnt(0)
	v_mfma_f32_16x16x32_bf16 v[12:15], v[0:3], v[4:7], v[44:47]
	ds_read_b128 v[4:7], v217 offset:55616
	v_pk_fma_f32 v[42:43], v[28:29], v[28:29], v[42:43]
	v_pk_fma_f32 v[40:41], v[30:31], v[30:31], v[40:41]
	s_waitcnt lgkmcnt(0)
	v_mfma_f32_16x16x32_bf16 v[8:11], v[0:3], v[4:7], v[32:35]
	ds_read_b128 v[4:7], v217 offset:57920
	s_nop 1
	ds_read_b128 v[32:35], v217 offset:60224
	v_mov_b32_e32 v44, v13
	s_waitcnt lgkmcnt(1)
	v_mfma_f32_16x16x32_bf16 v[4:7], v[0:3], v[4:7], v[36:39]
	s_nop 0
	v_mov_b32_e32 v45, v9
	s_nop 0
	v_mov_b32_e32 v38, v21
	v_mov_b32_e32 v39, v17
	s_waitcnt lgkmcnt(0)
	v_mfma_f32_16x16x32_bf16 v[0:3], v[0:3], v[32:35], v[48:51]
	v_and_b32_e32 v33, 64, v187
	v_xor_b32_e32 v32, 1, v187
	v_add_u32_e32 v33, 64, v33
	v_cmp_lt_i32_e32 vcc, v32, v33
	v_pk_mul_f32 v[38:39], v[38:39], v[38:39]
	v_mov_b32_e32 v34, v12
	v_cndmask_b32_e32 v32, v187, v32, vcc
	v_lshlrev_b32_e32 v52, 2, v32
	v_xor_b32_e32 v32, 2, v187
	v_cmp_lt_i32_e32 vcc, v32, v33
	v_mov_b32_e32 v35, v8
	v_mov_b32_e32 v48, v38
	v_cndmask_b32_e32 v32, v187, v32, vcc
	v_lshlrev_b32_e32 v53, 2, v32
	v_xor_b32_e32 v32, 4, v187
	v_cmp_lt_i32_e32 vcc, v32, v33
	v_pk_mul_f32 v[34:35], v[34:35], v[34:35]
	v_pk_mul_f32 v[44:45], v[44:45], v[44:45]
	v_cndmask_b32_e32 v32, v187, v32, vcc
	v_lshlrev_b32_e32 v54, 2, v32
	v_xor_b32_e32 v32, 8, v187
	v_cmp_lt_i32_e32 vcc, v32, v33
	v_mov_b32_e32 v33, v16
	v_mov_b32_e32 v36, v4
	v_cndmask_b32_e32 v32, v187, v32, vcc
	v_lshlrev_b32_e32 v55, 2, v32
	v_mov_b32_e32 v32, v20
	v_pk_mul_f32 v[32:33], v[32:33], v[32:33]
	v_mov_b32_e32 v37, v0
	v_mov_b32_e32 v49, v32
	v_pk_add_f32 v[42:43], v[42:43], v[48:49] op_sel:[1,0] op_sel_hi:[0,1]
	v_mov_b32_e32 v32, v39
	v_mov_b32_e32 v46, v5
	v_mov_b32_e32 v47, v1
	v_pk_add_f32 v[32:33], v[42:43], v[32:33]
	v_mov_b32_e32 v38, v44
	v_mov_b32_e32 v39, v34
	v_pk_mul_f32 v[36:37], v[36:37], v[36:37]
	v_pk_mul_f32 v[46:47], v[46:47], v[46:47]
	v_pk_add_f32 v[32:33], v[32:33], v[38:39]
	v_mov_b32_e32 v34, v45
	v_pk_add_f32 v[32:33], v[32:33], v[34:35]
	v_mov_b32_e32 v34, v46
	v_mov_b32_e32 v35, v36
	v_pk_add_f32 v[32:33], v[32:33], v[34:35]
	v_mov_b32_e32 v36, v47
	v_pk_add_f32 v[32:33], v[32:33], v[36:37]
	ds_bpermute_b32 v35, v52, v33
	ds_bpermute_b32 v34, v52, v32
	v_mov_b32_e32 v44, v23
	v_mov_b32_e32 v45, v19
	v_pk_mul_f32 v[44:45], v[44:45], v[44:45]
	v_mov_b32_e32 v46, v15
	s_waitcnt lgkmcnt(0)
	v_pk_add_f32 v[32:33], v[32:33], v[34:35]
	ds_bpermute_b32 v35, v53, v33
	ds_bpermute_b32 v34, v53, v32
	v_mov_b32_e32 v47, v11
	v_mov_b32_e32 v50, v44
	v_pk_mul_f32 v[46:47], v[46:47], v[46:47]
	v_mov_b32_e32 v38, v6
	s_waitcnt lgkmcnt(0)
	v_pk_add_f32 v[32:33], v[32:33], v[34:35]
	ds_bpermute_b32 v35, v54, v33
	ds_bpermute_b32 v34, v54, v32
	v_mov_b32_e32 v39, v2
	v_mov_b32_e32 v48, v7
	v_mov_b32_e32 v49, v3
	v_pk_mul_f32 v[38:39], v[38:39], v[38:39]
	s_waitcnt lgkmcnt(0)
	v_pk_add_f32 v[32:33], v[32:33], v[34:35]
	ds_bpermute_b32 v35, v55, v33
	ds_bpermute_b32 v34, v55, v32
	v_pk_mul_f32 v[48:49], v[48:49], v[48:49]
	s_waitcnt lgkmcnt(0)
	v_pk_add_f32 v[32:33], v[32:33], v[34:35]
	s_nop 0
	v_pk_fma_f32 v[36:37], v[32:33], s[4:5], v[90:91] op_sel_hi:[1,0,0]
	v_mov_b32_e32 v34, v14
	v_mul_f32_e32 v32, 0x4b800000, v37
	v_cmp_gt_f32_e32 vcc, s34, v37
	v_mov_b32_e32 v35, v10
	v_pk_mul_f32 v[34:35], v[34:35], v[34:35]
	v_cndmask_b32_e32 v32, v37, v32, vcc
	v_rsq_f32_e32 v32, v32
	v_cmp_gt_f32_e64 s[76:77], s34, v36
	v_mul_f32_e32 v33, 0x45800000, v32
	v_cndmask_b32_e32 v42, v32, v33, vcc
	v_mov_b32_e32 v32, v22
	v_mov_b32_e32 v33, v18
	v_pk_mul_f32 v[32:33], v[32:33], v[32:33]
	s_nop 0
	v_mov_b32_e32 v51, v32
	v_pk_add_f32 v[40:41], v[40:41], v[50:51] op_sel:[1,0] op_sel_hi:[0,1]
	v_mov_b32_e32 v32, v45
	v_pk_add_f32 v[32:33], v[40:41], v[32:33]
	v_mov_b32_e32 v40, v46
	v_mov_b32_e32 v41, v34
	v_pk_add_f32 v[32:33], v[32:33], v[40:41]
	v_mov_b32_e32 v34, v47
	v_pk_add_f32 v[32:33], v[32:33], v[34:35]
	v_mov_b32_e32 v34, v48
	v_mov_b32_e32 v35, v38
	v_pk_add_f32 v[32:33], v[32:33], v[34:35]
	v_mov_b32_e32 v38, v49
	v_pk_add_f32 v[32:33], v[32:33], v[38:39]
	ds_bpermute_b32 v35, v52, v33
	ds_bpermute_b32 v34, v52, v32
	s_waitcnt lgkmcnt(0)
	v_pk_add_f32 v[32:33], v[32:33], v[34:35]
	ds_bpermute_b32 v35, v53, v33
	ds_bpermute_b32 v34, v53, v32
	s_waitcnt lgkmcnt(0)
	v_pk_add_f32 v[32:33], v[32:33], v[34:35]
	ds_bpermute_b32 v35, v54, v33
	ds_bpermute_b32 v34, v54, v32
	s_waitcnt lgkmcnt(0)
	v_pk_add_f32 v[38:39], v[32:33], v[34:35]
	ds_bpermute_b32 v41, v55, v39
	ds_bpermute_b32 v40, v55, v38
	v_add_u32_e32 v34, s50, v201
	v_lshl_add_u64 v[32:33], v[120:121], 0, s[24:25]
	v_ashrrev_i32_e32 v35, 31, v34
	s_and_saveexec_b64 s[26:27], s[74:75]
	s_cbranch_execz .LBB0_582
; DEVI float b2f(bfu b) { return __uint_as_float(((unsigned)b) << 16); }
; DEVI float siluf_(float x) { return x / (1.f + __expf(-x)); }
; DEVI void h3_item(const Params& P, int l, int ck, int h, char* smem, int tid) {
;     ...
;   float rinv[4];
; #pragma unroll
;   for (int j = 0; j < 4; ++j) {
;     float ss = 0.f;
; #pragma unroll
;     for (int n = 0; n < 8; ++n) ss += o[n][j] * o[n][j];
;     ss += __shfl_xor(ss, 1); ss += __shfl_xor(ss, 2); ss += __shfl_xor(ss, 4); ss += __shfl_xor(ss, 8);
;     rinv[j] = rsqrtf(ss * (1.f / 128.f) + 1e-6f);
;   }
;   const float* ng = P.in[17] + l * 128;
;   bfu* UC = (bfu*)(P.ws + O_UC);
; #pragma unroll
;   for (int n = 0; n < 8; ++n)
; #pragma unroll
;     for (int j = 0; j < 4; ++j) {
;       int t = 16 * w + fq * 4 + j, e = n * 16 + fr;
;       if (t < L) {
;         float g = b2f(QT[t * 136 + e]);
;         UC[(long)(ci.lt0 + t) * 1024 + h * 128 + e] = f2b(o[n][j] * rinv[j] * ng[e] * siluf_(g));
;       }
;     }
	ds_read_u16 v37, v218
	v_mul_f32_e32 v28, v28, v42
	s_waitcnt lgkmcnt(0)
	v_lshlrev_b32_e32 v37, 16, v37
	v_mul_f32_e32 v28, v28, v219
	v_mul_f32_e32 v43, 0xbfb8aa3b, v37
	v_exp_f32_e32 v43, v43
	s_nop 0
	v_add_f32_e32 v43, 1.0, v43
	v_div_scale_f32 v44, s[52:53], v43, v43, v37
	v_rcp_f32_e32 v45, v44
	s_nop 0
	v_fma_f32 v46, -v44, v45, 1.0
	v_fmac_f32_e32 v45, v46, v45
	v_div_scale_f32 v46, vcc, v37, v43, v37
	v_mul_f32_e32 v47, v46, v45
	v_fma_f32 v48, -v44, v47, v46
	v_fmac_f32_e32 v47, v48, v45
	v_fma_f32 v44, -v44, v47, v46
	v_div_fmas_f32 v44, v44, v45, v47
	v_div_fixup_f32 v37, v44, v43, v37
	v_mul_f32_e32 v28, v28, v37
	v_bfe_u32 v37, v28, 16, 1
	v_lshlrev_b64 v[44:45], 11, v[34:35]
	v_add3_u32 v28, v28, v37, s39
	v_lshl_add_u64 v[44:45], v[32:33], 0, v[44:45]
	global_store_short_d16_hi v[44:45], v28, off
.LBB0_582:
	s_or_b64 exec, exec, s[26:27]
	v_mul_f32_e32 v28, 0x4b800000, v36
	v_cndmask_b32_e64 v28, v36, v28, s[76:77]
	v_rsq_f32_e32 v28, v28
	s_nop 0
	v_mul_f32_e32 v36, 0x45800000, v28
	v_cndmask_b32_e64 v43, v28, v36, s[76:77]
	v_add_u32_e32 v36, s50, v202
	v_cmp_gt_i32_e64 s[76:77], s51, v202
	v_ashrrev_i32_e32 v37, 31, v36
	s_and_saveexec_b64 s[26:27], s[76:77]
	s_cbranch_execz .LBB0_584
	ds_read_u16 v28, v218 offset:272
	v_mul_f32_e32 v29, v29, v43
	s_waitcnt lgkmcnt(0)
	v_lshlrev_b32_e32 v28, 16, v28
	v_mul_f32_e32 v29, v29, v219
	v_mul_f32_e32 v44, 0xbfb8aa3b, v28
	v_exp_f32_e32 v44, v44
	s_nop 0
	v_add_f32_e32 v44, 1.0, v44
	v_div_scale_f32 v45, s[52:53], v44, v44, v28
	v_rcp_f32_e32 v46, v45
	s_nop 0
	v_fma_f32 v47, -v45, v46, 1.0
	v_fmac_f32_e32 v46, v47, v46
	v_div_scale_f32 v47, vcc, v28, v44, v28
	v_mul_f32_e32 v48, v47, v46
	v_fma_f32 v49, -v45, v48, v47
	v_fmac_f32_e32 v48, v49, v46
	v_fma_f32 v45, -v45, v48, v47
	v_div_fmas_f32 v45, v45, v46, v48
	v_div_fixup_f32 v28, v45, v44, v28
	v_mul_f32_e32 v28, v29, v28
	v_bfe_u32 v29, v28, 16, 1
	v_add3_u32 v44, v28, v29, s39
	v_lshlrev_b64 v[28:29], 11, v[36:37]
	v_lshl_add_u64 v[28:29], v[32:33], 0, v[28:29]
	global_store_short_d16_hi v[28:29], v44, off
.LBB0_584:
	s_or_b64 exec, exec, s[26:27]
	s_waitcnt lgkmcnt(0)
	v_pk_add_f32 v[28:29], v[38:39], v[40:41]
	v_cmp_gt_i32_e64 s[78:79], s51, v203
	v_pk_fma_f32 v[38:39], v[28:29], s[4:5], v[90:91] op_sel_hi:[1,0,0]
	s_nop 0
	v_mul_f32_e32 v28, 0x4b800000, v39
	v_cmp_gt_f32_e32 vcc, s34, v39
	v_cmp_gt_f32_e64 s[80:81], s34, v38
	s_nop 0
	v_cndmask_b32_e32 v28, v39, v28, vcc
	v_rsq_f32_e32 v28, v28
	s_nop 0
	v_mul_f32_e32 v29, 0x45800000, v28
	v_cndmask_b32_e32 v40, v28, v29, vcc
	v_add_u32_e32 v28, s50, v203
	v_ashrrev_i32_e32 v29, 31, v28
	s_and_saveexec_b64 s[26:27], s[78:79]
	s_cbranch_execz .LBB0_586
	ds_read_u16 v39, v218 offset:544
	v_mul_f32_e32 v30, v30, v40
	s_waitcnt lgkmcnt(0)
	v_lshlrev_b32_e32 v39, 16, v39
	v_mul_f32_e32 v30, v30, v219
	v_mul_f32_e32 v41, 0xbfb8aa3b, v39
	v_exp_f32_e32 v41, v41
	s_nop 0
	v_add_f32_e32 v41, 1.0, v41
	v_div_scale_f32 v44, s[52:53], v41, v41, v39
	v_rcp_f32_e32 v45, v44
	s_nop 0
	v_fma_f32 v46, -v44, v45, 1.0
	v_fmac_f32_e32 v45, v46, v45
	v_div_scale_f32 v46, vcc, v39, v41, v39
	v_mul_f32_e32 v47, v46, v45
	v_fma_f32 v48, -v44, v47, v46
	v_fmac_f32_e32 v47, v48, v45
	v_fma_f32 v44, -v44, v47, v46
	v_div_fmas_f32 v44, v44, v45, v47
	v_div_fixup_f32 v39, v44, v41, v39
	v_mul_f32_e32 v30, v30, v39
	v_bfe_u32 v39, v30, 16, 1
	v_lshlrev_b64 v[44:45], 11, v[28:29]
	v_add3_u32 v30, v30, v39, s39
	v_lshl_add_u64 v[44:45], v[32:33], 0, v[44:45]
	global_store_short_d16_hi v[44:45], v30, off
.LBB0_586:
	s_or_b64 exec, exec, s[26:27]
	v_mul_f32_e32 v30, 0x4b800000, v38
	v_cndmask_b32_e64 v30, v38, v30, s[80:81]
	v_rsq_f32_e32 v30, v30
	s_nop 0
	v_mul_f32_e32 v38, 0x45800000, v30
	v_cndmask_b32_e64 v30, v30, v38, s[80:81]
	v_add_u32_e32 v38, s50, v204
	v_cmp_gt_i32_e64 s[80:81], s51, v204
	v_ashrrev_i32_e32 v39, 31, v38
	s_and_saveexec_b64 s[26:27], s[80:81]
	s_cbranch_execz .LBB0_617
	ds_read_u16 v41, v218 offset:816
	v_mul_f32_e32 v31, v31, v30
	s_waitcnt lgkmcnt(0)
	v_lshlrev_b32_e32 v41, 16, v41
	v_mul_f32_e32 v31, v31, v219
	v_mul_f32_e32 v44, 0xbfb8aa3b, v41
	v_exp_f32_e32 v44, v44
	s_nop 0
	v_add_f32_e32 v44, 1.0, v44
	v_div_scale_f32 v45, s[50:51], v44, v44, v41
	v_rcp_f32_e32 v46, v45
	s_nop 0
	v_fma_f32 v47, -v45, v46, 1.0
	v_fmac_f32_e32 v46, v47, v46
	v_div_scale_f32 v47, vcc, v41, v44, v41
	v_mul_f32_e32 v48, v47, v46
	v_fma_f32 v49, -v45, v48, v47
	v_fmac_f32_e32 v48, v49, v46
	v_fma_f32 v45, -v45, v48, v47
	v_div_fmas_f32 v45, v45, v46, v48
	v_div_fixup_f32 v41, v45, v44, v41
	v_mul_f32_e32 v31, v31, v41
	v_bfe_u32 v41, v31, 16, 1
	v_lshlrev_b64 v[44:45], 11, v[38:39]
	v_add3_u32 v31, v31, v41, s39
	v_lshl_add_u64 v[44:45], v[32:33], 0, v[44:45]
	global_store_short_d16_hi v[44:45], v31, off
	s_or_b64 exec, exec, s[26:27]
	s_and_saveexec_b64 s[26:27], s[74:75]
	s_cbranch_execnz .LBB0_618

; DEVI float b2f(bfu b) { return __uint_as_float(((unsigned)b) << 16); }
; DEVI float siluf_(float x) { return x / (1.f + __expf(-x)); }
; DEVI void h3_item(const Params& P, int l, int ck, int h, char* smem, int tid) {
;     ...
;   bfu* UC = (bfu*)(P.ws + O_UC);
; #pragma unroll
;   for (int n = 0; n < 8; ++n)
; #pragma unroll
;     for (int j = 0; j < 4; ++j) {
;       int t = 16 * w + fq * 4 + j, e = n * 16 + fr;
;       if (t < L) {
;         float g = b2f(QT[t * 136 + e]);
;         UC[(long)(ci.lt0 + t) * 1024 + h * 128 + e] = f2b(o[n][j] * rinv[j] * ng[e] * siluf_(g));
;       }
;     }
.LBB0_589:
	ds_read_u16 v24, v218 offset:304
	v_mul_f32_e32 v25, v25, v43
	s_waitcnt lgkmcnt(0)
	v_lshlrev_b32_e32 v24, 16, v24
	v_mul_f32_e32 v25, v25, v220
	v_mul_f32_e32 v31, 0xbfb8aa3b, v24
	v_exp_f32_e32 v31, v31
	s_nop 0
	v_add_f32_e32 v31, 1.0, v31
	v_div_scale_f32 v41, s[50:51], v31, v31, v24
	v_rcp_f32_e32 v44, v41
	s_nop 0
	v_fma_f32 v45, -v41, v44, 1.0
	v_fmac_f32_e32 v44, v45, v44
	v_div_scale_f32 v45, vcc, v24, v31, v24
	v_mul_f32_e32 v46, v45, v44
	v_fma_f32 v47, -v41, v46, v45
	v_fmac_f32_e32 v46, v47, v44
	v_fma_f32 v41, -v41, v46, v45
	v_div_fmas_f32 v41, v41, v44, v46
	v_div_fixup_f32 v24, v41, v31, v24
	v_mul_f32_e32 v24, v25, v24
	v_bfe_u32 v25, v24, 16, 1
	v_add3_u32 v31, v24, v25, s39
	v_lshlrev_b64 v[24:25], 11, v[36:37]
	v_lshl_add_u64 v[24:25], v[32:33], 0, v[24:25]
	global_store_short_d16_hi v[24:25], v31, off offset:32
	s_or_b64 exec, exec, s[26:27]
	s_and_saveexec_b64 s[26:27], s[78:79]
	s_cbranch_execnz .LBB0_620

; DEVI float b2f(bfu b) { return __uint_as_float(((unsigned)b) << 16); }
; DEVI float siluf_(float x) { return x / (1.f + __expf(-x)); }
; DEVI void h3_item(const Params& P, int l, int ck, int h, char* smem, int tid) {
;     ...
;   bfu* UC = (bfu*)(P.ws + O_UC);
; #pragma unroll
;   for (int n = 0; n < 8; ++n)
; #pragma unroll
;     for (int j = 0; j < 4; ++j) {
;       int t = 16 * w + fq * 4 + j, e = n * 16 + fr;
;       if (t < L) {
;         float g = b2f(QT[t * 136 + e]);
;         UC[(long)(ci.lt0 + t) * 1024 + h * 128 + e] = f2b(o[n][j] * rinv[j] * ng[e] * siluf_(g));
;       }
;     }
.LBB0_591:
	ds_read_u16 v24, v218 offset:848
	v_mul_f32_e32 v25, v27, v30
	s_waitcnt lgkmcnt(0)
	v_lshlrev_b32_e32 v24, 16, v24
	v_mul_f32_e32 v25, v25, v220
	v_mul_f32_e32 v26, 0xbfb8aa3b, v24
	v_exp_f32_e32 v26, v26
	s_nop 0
	v_add_f32_e32 v26, 1.0, v26
	v_div_scale_f32 v27, s[50:51], v26, v26, v24
	v_rcp_f32_e32 v31, v27
	s_nop 0
	v_fma_f32 v41, -v27, v31, 1.0
	v_fmac_f32_e32 v31, v41, v31
	v_div_scale_f32 v41, vcc, v24, v26, v24
	v_mul_f32_e32 v44, v41, v31
	v_fma_f32 v45, -v27, v44, v41
	v_fmac_f32_e32 v44, v45, v31
	v_fma_f32 v27, -v27, v44, v41
	v_div_fmas_f32 v27, v27, v31, v44
	v_div_fixup_f32 v24, v27, v26, v24
	v_mul_f32_e32 v24, v25, v24
	v_bfe_u32 v25, v24, 16, 1
	v_add3_u32 v26, v24, v25, s39
	v_lshlrev_b64 v[24:25], 11, v[38:39]
	v_lshl_add_u64 v[24:25], v[32:33], 0, v[24:25]
	global_store_short_d16_hi v[24:25], v26, off offset:32
	s_or_b64 exec, exec, s[26:27]
	s_and_saveexec_b64 s[26:27], s[74:75]
	s_cbranch_execnz .LBB0_622

; DEVI float b2f(bfu b) { return __uint_as_float(((unsigned)b) << 16); }
; DEVI float siluf_(float x) { return x / (1.f + __expf(-x)); }
; DEVI void h3_item(const Params& P, int l, int ck, int h, char* smem, int tid) {
;     ...
;   bfu* UC = (bfu*)(P.ws + O_UC);
; #pragma unroll
;   for (int n = 0; n < 8; ++n)
; #pragma unroll
;     for (int j = 0; j < 4; ++j) {
;       int t = 16 * w + fq * 4 + j, e = n * 16 + fr;
;       if (t < L) {
;         float g = b2f(QT[t * 136 + e]);
;         UC[(long)(ci.lt0 + t) * 1024 + h * 128 + e] = f2b(o[n][j] * rinv[j] * ng[e] * siluf_(g));
;       }
;     }
.LBB0_593:
	ds_read_u16 v20, v218 offset:336
	v_mul_f32_e32 v21, v21, v43
	s_waitcnt lgkmcnt(0)
	v_lshlrev_b32_e32 v20, 16, v20
	v_mul_f32_e32 v21, v21, v221
	v_mul_f32_e32 v24, 0xbfb8aa3b, v20
	v_exp_f32_e32 v24, v24
	s_nop 0
	v_add_f32_e32 v24, 1.0, v24
	v_div_scale_f32 v25, s[50:51], v24, v24, v20
	v_rcp_f32_e32 v26, v25
	s_nop 0
	v_fma_f32 v27, -v25, v26, 1.0
	v_fmac_f32_e32 v26, v27, v26
	v_div_scale_f32 v27, vcc, v20, v24, v20
	v_mul_f32_e32 v31, v27, v26
	v_fma_f32 v41, -v25, v31, v27
	v_fmac_f32_e32 v31, v41, v26
	v_fma_f32 v25, -v25, v31, v27
	v_div_fmas_f32 v25, v25, v26, v31
	v_div_fixup_f32 v20, v25, v24, v20
	v_mul_f32_e32 v20, v21, v20
	v_bfe_u32 v21, v20, 16, 1
	v_add3_u32 v24, v20, v21, s39
	v_lshlrev_b64 v[20:21], 11, v[36:37]
	v_lshl_add_u64 v[20:21], v[32:33], 0, v[20:21]
	global_store_short_d16_hi v[20:21], v24, off offset:64
	s_or_b64 exec, exec, s[26:27]
	s_and_saveexec_b64 s[26:27], s[78:79]
	s_cbranch_execnz .LBB0_624

; DEVI float b2f(bfu b) { return __uint_as_float(((unsigned)b) << 16); }
; DEVI float siluf_(float x) { return x / (1.f + __expf(-x)); }
; DEVI void h3_item(const Params& P, int l, int ck, int h, char* smem, int tid) {
;     ...
;   bfu* UC = (bfu*)(P.ws + O_UC);
; #pragma unroll
;   for (int n = 0; n < 8; ++n)
; #pragma unroll
;     for (int j = 0; j < 4; ++j) {
;       int t = 16 * w + fq * 4 + j, e = n * 16 + fr;
;       if (t < L) {
;         float g = b2f(QT[t * 136 + e]);
;         UC[(long)(ci.lt0 + t) * 1024 + h * 128 + e] = f2b(o[n][j] * rinv[j] * ng[e] * siluf_(g));
;       }
;     }
.LBB0_595:
	ds_read_u16 v20, v218 offset:880
	v_mul_f32_e32 v21, v23, v30
	s_waitcnt lgkmcnt(0)
	v_lshlrev_b32_e32 v20, 16, v20
	v_mul_f32_e32 v21, v21, v221
	v_mul_f32_e32 v22, 0xbfb8aa3b, v20
	v_exp_f32_e32 v22, v22
	s_nop 0
	v_add_f32_e32 v22, 1.0, v22
	v_div_scale_f32 v23, s[50:51], v22, v22, v20
	v_rcp_f32_e32 v24, v23
	s_nop 0
	v_fma_f32 v25, -v23, v24, 1.0
	v_fmac_f32_e32 v24, v25, v24
	v_div_scale_f32 v25, vcc, v20, v22, v20
	v_mul_f32_e32 v26, v25, v24
	v_fma_f32 v27, -v23, v26, v25
	v_fmac_f32_e32 v26, v27, v24
	v_fma_f32 v23, -v23, v26, v25
	v_div_fmas_f32 v23, v23, v24, v26
	v_div_fixup_f32 v20, v23, v22, v20
	v_mul_f32_e32 v20, v21, v20
	v_bfe_u32 v21, v20, 16, 1
	v_add3_u32 v22, v20, v21, s39
	v_lshlrev_b64 v[20:21], 11, v[38:39]
	v_lshl_add_u64 v[20:21], v[32:33], 0, v[20:21]
	global_store_short_d16_hi v[20:21], v22, off offset:64
	s_or_b64 exec, exec, s[26:27]
	s_and_saveexec_b64 s[26:27], s[74:75]
	s_cbranch_execnz .LBB0_626

; DEVI float b2f(bfu b) { return __uint_as_float(((unsigned)b) << 16); }
; DEVI float siluf_(float x) { return x / (1.f + __expf(-x)); }
; DEVI void h3_item(const Params& P, int l, int ck, int h, char* smem, int tid) {
;     ...
;   bfu* UC = (bfu*)(P.ws + O_UC);
; #pragma unroll
;   for (int n = 0; n < 8; ++n)
; #pragma unroll
;     for (int j = 0; j < 4; ++j) {
;       int t = 16 * w + fq * 4 + j, e = n * 16 + fr;
;       if (t < L) {
;         float g = b2f(QT[t * 136 + e]);
;         UC[(long)(ci.lt0 + t) * 1024 + h * 128 + e] = f2b(o[n][j] * rinv[j] * ng[e] * siluf_(g));
;       }
;     }
.LBB0_597:
	ds_read_u16 v16, v218 offset:368
	v_mul_f32_e32 v17, v17, v43
	s_waitcnt lgkmcnt(0)
	v_lshlrev_b32_e32 v16, 16, v16
	v_mul_f32_e32 v17, v17, v222
	v_mul_f32_e32 v20, 0xbfb8aa3b, v16
	v_exp_f32_e32 v20, v20
	s_nop 0
	v_add_f32_e32 v20, 1.0, v20
	v_div_scale_f32 v21, s[50:51], v20, v20, v16
	v_rcp_f32_e32 v22, v21
	s_nop 0
	v_fma_f32 v23, -v21, v22, 1.0
	v_fmac_f32_e32 v22, v23, v22
	v_div_scale_f32 v23, vcc, v16, v20, v16
	v_mul_f32_e32 v24, v23, v22
	v_fma_f32 v25, -v21, v24, v23
	v_fmac_f32_e32 v24, v25, v22
	v_fma_f32 v21, -v21, v24, v23
	v_div_fmas_f32 v21, v21, v22, v24
	v_div_fixup_f32 v16, v21, v20, v16
	v_mul_f32_e32 v16, v17, v16
	v_bfe_u32 v17, v16, 16, 1
	v_add3_u32 v20, v16, v17, s39
	v_lshlrev_b64 v[16:17], 11, v[36:37]
	v_lshl_add_u64 v[16:17], v[32:33], 0, v[16:17]
	global_store_short_d16_hi v[16:17], v20, off offset:96
	s_or_b64 exec, exec, s[26:27]
	s_and_saveexec_b64 s[26:27], s[78:79]
	s_cbranch_execnz .LBB0_628

; DEVI float b2f(bfu b) { return __uint_as_float(((unsigned)b) << 16); }
; DEVI float siluf_(float x) { return x / (1.f + __expf(-x)); }
; DEVI void h3_item(const Params& P, int l, int ck, int h, char* smem, int tid) {
;     ...
;   bfu* UC = (bfu*)(P.ws + O_UC);
; #pragma unroll
;   for (int n = 0; n < 8; ++n)
; #pragma unroll
;     for (int j = 0; j < 4; ++j) {
;       int t = 16 * w + fq * 4 + j, e = n * 16 + fr;
;       if (t < L) {
;         float g = b2f(QT[t * 136 + e]);
;         UC[(long)(ci.lt0 + t) * 1024 + h * 128 + e] = f2b(o[n][j] * rinv[j] * ng[e] * siluf_(g));
;       }
;     }
.LBB0_599:
	ds_read_u16 v16, v218 offset:912
	v_mul_f32_e32 v17, v19, v30
	s_waitcnt lgkmcnt(0)
	v_lshlrev_b32_e32 v16, 16, v16
	v_mul_f32_e32 v17, v17, v222
	v_mul_f32_e32 v18, 0xbfb8aa3b, v16
	v_exp_f32_e32 v18, v18
	s_nop 0
	v_add_f32_e32 v18, 1.0, v18
	v_div_scale_f32 v19, s[50:51], v18, v18, v16
	v_rcp_f32_e32 v20, v19
	s_nop 0
	v_fma_f32 v21, -v19, v20, 1.0
	v_fmac_f32_e32 v20, v21, v20
	v_div_scale_f32 v21, vcc, v16, v18, v16
	v_mul_f32_e32 v22, v21, v20
	v_fma_f32 v23, -v19, v22, v21
	v_fmac_f32_e32 v22, v23, v20
	v_fma_f32 v19, -v19, v22, v21
	v_div_fmas_f32 v19, v19, v20, v22
	v_div_fixup_f32 v16, v19, v18, v16
	v_mul_f32_e32 v16, v17, v16
	v_bfe_u32 v17, v16, 16, 1
	v_add3_u32 v18, v16, v17, s39
	v_lshlrev_b64 v[16:17], 11, v[38:39]
	v_lshl_add_u64 v[16:17], v[32:33], 0, v[16:17]
	global_store_short_d16_hi v[16:17], v18, off offset:96
	s_or_b64 exec, exec, s[26:27]
	s_and_saveexec_b64 s[26:27], s[74:75]
	s_cbranch_execnz .LBB0_630

; DEVI float b2f(bfu b) { return __uint_as_float(((unsigned)b) << 16); }
; DEVI float siluf_(float x) { return x / (1.f + __expf(-x)); }
; DEVI void h3_item(const Params& P, int l, int ck, int h, char* smem, int tid) {
;     ...
;   bfu* UC = (bfu*)(P.ws + O_UC);
; #pragma unroll
;   for (int n = 0; n < 8; ++n)
; #pragma unroll
;     for (int j = 0; j < 4; ++j) {
;       int t = 16 * w + fq * 4 + j, e = n * 16 + fr;
;       if (t < L) {
;         float g = b2f(QT[t * 136 + e]);
;         UC[(long)(ci.lt0 + t) * 1024 + h * 128 + e] = f2b(o[n][j] * rinv[j] * ng[e] * siluf_(g));
;       }
;     }
.LBB0_601:
	ds_read_u16 v12, v218 offset:400
	v_mul_f32_e32 v13, v13, v43
	s_waitcnt lgkmcnt(0)
	v_lshlrev_b32_e32 v12, 16, v12
	v_mul_f32_e32 v13, v13, v223
	v_mul_f32_e32 v16, 0xbfb8aa3b, v12
	v_exp_f32_e32 v16, v16
	s_nop 0
	v_add_f32_e32 v16, 1.0, v16
	v_div_scale_f32 v17, s[50:51], v16, v16, v12
	v_rcp_f32_e32 v18, v17
	s_nop 0
	v_fma_f32 v19, -v17, v18, 1.0
	v_fmac_f32_e32 v18, v19, v18
	v_div_scale_f32 v19, vcc, v12, v16, v12
	v_mul_f32_e32 v20, v19, v18
	v_fma_f32 v21, -v17, v20, v19
	v_fmac_f32_e32 v20, v21, v18
	v_fma_f32 v17, -v17, v20, v19
	v_div_fmas_f32 v17, v17, v18, v20
	v_div_fixup_f32 v12, v17, v16, v12
	v_mul_f32_e32 v12, v13, v12
	v_bfe_u32 v13, v12, 16, 1
	v_add3_u32 v16, v12, v13, s39
	v_lshlrev_b64 v[12:13], 11, v[36:37]
	v_lshl_add_u64 v[12:13], v[32:33], 0, v[12:13]
	global_store_short_d16_hi v[12:13], v16, off offset:128
	s_or_b64 exec, exec, s[26:27]
	s_and_saveexec_b64 s[26:27], s[78:79]
	s_cbranch_execnz .LBB0_632

; DEVI float b2f(bfu b) { return __uint_as_float(((unsigned)b) << 16); }
; DEVI float siluf_(float x) { return x / (1.f + __expf(-x)); }
; DEVI void h3_item(const Params& P, int l, int ck, int h, char* smem, int tid) {
;     ...
;   bfu* UC = (bfu*)(P.ws + O_UC);
; #pragma unroll
;   for (int n = 0; n < 8; ++n)
; #pragma unroll
;     for (int j = 0; j < 4; ++j) {
;       int t = 16 * w + fq * 4 + j, e = n * 16 + fr;
;       if (t < L) {
;         float g = b2f(QT[t * 136 + e]);
;         UC[(long)(ci.lt0 + t) * 1024 + h * 128 + e] = f2b(o[n][j] * rinv[j] * ng[e] * siluf_(g));
;       }
;     }
.LBB0_603:
	ds_read_u16 v12, v218 offset:944
	v_mul_f32_e32 v13, v15, v30
	s_waitcnt lgkmcnt(0)
	v_lshlrev_b32_e32 v12, 16, v12
	v_mul_f32_e32 v13, v13, v223
	v_mul_f32_e32 v14, 0xbfb8aa3b, v12
	v_exp_f32_e32 v14, v14
	s_nop 0
	v_add_f32_e32 v14, 1.0, v14
	v_div_scale_f32 v15, s[50:51], v14, v14, v12
	v_rcp_f32_e32 v16, v15
	s_nop 0
	v_fma_f32 v17, -v15, v16, 1.0
	v_fmac_f32_e32 v16, v17, v16
	v_div_scale_f32 v17, vcc, v12, v14, v12
	v_mul_f32_e32 v18, v17, v16
	v_fma_f32 v19, -v15, v18, v17
	v_fmac_f32_e32 v18, v19, v16
	v_fma_f32 v15, -v15, v18, v17
	v_div_fmas_f32 v15, v15, v16, v18
	v_div_fixup_f32 v12, v15, v14, v12
	v_mul_f32_e32 v12, v13, v12
	v_bfe_u32 v13, v12, 16, 1
	v_add3_u32 v14, v12, v13, s39
	v_lshlrev_b64 v[12:13], 11, v[38:39]
	v_lshl_add_u64 v[12:13], v[32:33], 0, v[12:13]
	global_store_short_d16_hi v[12:13], v14, off offset:128
	s_or_b64 exec, exec, s[26:27]
	s_and_saveexec_b64 s[26:27], s[74:75]
	s_cbranch_execnz .LBB0_634

; DEVI float b2f(bfu b) { return __uint_as_float(((unsigned)b) << 16); }
; DEVI float siluf_(float x) { return x / (1.f + __expf(-x)); }
; DEVI void h3_item(const Params& P, int l, int ck, int h, char* smem, int tid) {
;     ...
;   bfu* UC = (bfu*)(P.ws + O_UC);
; #pragma unroll
;   for (int n = 0; n < 8; ++n)
; #pragma unroll
;     for (int j = 0; j < 4; ++j) {
;       int t = 16 * w + fq * 4 + j, e = n * 16 + fr;
;       if (t < L) {
;         float g = b2f(QT[t * 136 + e]);
;         UC[(long)(ci.lt0 + t) * 1024 + h * 128 + e] = f2b(o[n][j] * rinv[j] * ng[e] * siluf_(g));
;       }
;     }
.LBB0_605:
	ds_read_u16 v8, v218 offset:432
	v_mul_f32_e32 v9, v9, v43
	s_waitcnt lgkmcnt(0)
	v_lshlrev_b32_e32 v8, 16, v8
	v_mul_f32_e32 v9, v9, v224
	v_mul_f32_e32 v12, 0xbfb8aa3b, v8
	v_exp_f32_e32 v12, v12
	s_nop 0
	v_add_f32_e32 v12, 1.0, v12
	v_div_scale_f32 v13, s[50:51], v12, v12, v8
	v_rcp_f32_e32 v14, v13
	s_nop 0
	v_fma_f32 v15, -v13, v14, 1.0
	v_fmac_f32_e32 v14, v15, v14
	v_div_scale_f32 v15, vcc, v8, v12, v8
	v_mul_f32_e32 v16, v15, v14
	v_fma_f32 v17, -v13, v16, v15
	v_fmac_f32_e32 v16, v17, v14
	v_fma_f32 v13, -v13, v16, v15
	v_div_fmas_f32 v13, v13, v14, v16
	v_div_fixup_f32 v8, v13, v12, v8
	v_mul_f32_e32 v8, v9, v8
	v_bfe_u32 v9, v8, 16, 1
	v_add3_u32 v12, v8, v9, s39
	v_lshlrev_b64 v[8:9], 11, v[36:37]
	v_lshl_add_u64 v[8:9], v[32:33], 0, v[8:9]
	global_store_short_d16_hi v[8:9], v12, off offset:160
	s_or_b64 exec, exec, s[26:27]
	s_and_saveexec_b64 s[26:27], s[78:79]
	s_cbranch_execnz .LBB0_636

; DEVI float b2f(bfu b) { return __uint_as_float(((unsigned)b) << 16); }
; DEVI float siluf_(float x) { return x / (1.f + __expf(-x)); }
; DEVI void h3_item(const Params& P, int l, int ck, int h, char* smem, int tid) {
;     ...
;   bfu* UC = (bfu*)(P.ws + O_UC);
; #pragma unroll
;   for (int n = 0; n < 8; ++n)
; #pragma unroll
;     for (int j = 0; j < 4; ++j) {
;       int t = 16 * w + fq * 4 + j, e = n * 16 + fr;
;       if (t < L) {
;         float g = b2f(QT[t * 136 + e]);
;         UC[(long)(ci.lt0 + t) * 1024 + h * 128 + e] = f2b(o[n][j] * rinv[j] * ng[e] * siluf_(g));
;       }
;     }
.LBB0_607:
	ds_read_u16 v8, v218 offset:976
	v_mul_f32_e32 v9, v11, v30
	s_waitcnt lgkmcnt(0)
	v_lshlrev_b32_e32 v8, 16, v8
	v_mul_f32_e32 v9, v9, v224
	v_mul_f32_e32 v10, 0xbfb8aa3b, v8
	v_exp_f32_e32 v10, v10
	s_nop 0
	v_add_f32_e32 v10, 1.0, v10
	v_div_scale_f32 v11, s[50:51], v10, v10, v8
	v_rcp_f32_e32 v12, v11
	s_nop 0
	v_fma_f32 v13, -v11, v12, 1.0
	v_fmac_f32_e32 v12, v13, v12
	v_div_scale_f32 v13, vcc, v8, v10, v8
	v_mul_f32_e32 v14, v13, v12
	v_fma_f32 v15, -v11, v14, v13
	v_fmac_f32_e32 v14, v15, v12
	v_fma_f32 v11, -v11, v14, v13
	v_div_fmas_f32 v11, v11, v12, v14
	v_div_fixup_f32 v8, v11, v10, v8
	v_mul_f32_e32 v8, v9, v8
	v_bfe_u32 v9, v8, 16, 1
	v_add3_u32 v10, v8, v9, s39
	v_lshlrev_b64 v[8:9], 11, v[38:39]
	v_lshl_add_u64 v[8:9], v[32:33], 0, v[8:9]
	global_store_short_d16_hi v[8:9], v10, off offset:160
	s_or_b64 exec, exec, s[26:27]
	s_and_saveexec_b64 s[26:27], s[74:75]
	s_cbranch_execnz .LBB0_638

; DEVI float b2f(bfu b) { return __uint_as_float(((unsigned)b) << 16); }
; DEVI float siluf_(float x) { return x / (1.f + __expf(-x)); }
; DEVI void h3_item(const Params& P, int l, int ck, int h, char* smem, int tid) {
;     ...
;   bfu* UC = (bfu*)(P.ws + O_UC);
; #pragma unroll
;   for (int n = 0; n < 8; ++n)
; #pragma unroll
;     for (int j = 0; j < 4; ++j) {
;       int t = 16 * w + fq * 4 + j, e = n * 16 + fr;
;       if (t < L) {
;         float g = b2f(QT[t * 136 + e]);
;         UC[(long)(ci.lt0 + t) * 1024 + h * 128 + e] = f2b(o[n][j] * rinv[j] * ng[e] * siluf_(g));
;       }
;     }
.LBB0_609:
	ds_read_u16 v4, v218 offset:464
	v_mul_f32_e32 v5, v5, v43
	s_waitcnt lgkmcnt(0)
	v_lshlrev_b32_e32 v4, 16, v4
	v_mul_f32_e32 v5, v5, v225
	v_mul_f32_e32 v8, 0xbfb8aa3b, v4
	v_exp_f32_e32 v8, v8
	s_nop 0
	v_add_f32_e32 v8, 1.0, v8
	v_div_scale_f32 v9, s[50:51], v8, v8, v4
	v_rcp_f32_e32 v10, v9
	s_nop 0
	v_fma_f32 v11, -v9, v10, 1.0
	v_fmac_f32_e32 v10, v11, v10
	v_div_scale_f32 v11, vcc, v4, v8, v4
	v_mul_f32_e32 v12, v11, v10
	v_fma_f32 v13, -v9, v12, v11
	v_fmac_f32_e32 v12, v13, v10
	v_fma_f32 v9, -v9, v12, v11
	v_div_fmas_f32 v9, v9, v10, v12
	v_div_fixup_f32 v4, v9, v8, v4
	v_mul_f32_e32 v4, v5, v4
	v_bfe_u32 v5, v4, 16, 1
	v_add3_u32 v8, v4, v5, s39
	v_lshlrev_b64 v[4:5], 11, v[36:37]
	v_lshl_add_u64 v[4:5], v[32:33], 0, v[4:5]
	global_store_short_d16_hi v[4:5], v8, off offset:192
	s_or_b64 exec, exec, s[26:27]
	s_and_saveexec_b64 s[26:27], s[78:79]
	s_cbranch_execnz .LBB0_640

; DEVI float b2f(bfu b) { return __uint_as_float(((unsigned)b) << 16); }
; DEVI float siluf_(float x) { return x / (1.f + __expf(-x)); }
; DEVI void h3_item(const Params& P, int l, int ck, int h, char* smem, int tid) {
;     ...
;   bfu* UC = (bfu*)(P.ws + O_UC);
; #pragma unroll
;   for (int n = 0; n < 8; ++n)
; #pragma unroll
;     for (int j = 0; j < 4; ++j) {
;       int t = 16 * w + fq * 4 + j, e = n * 16 + fr;
;       if (t < L) {
;         float g = b2f(QT[t * 136 + e]);
;         UC[(long)(ci.lt0 + t) * 1024 + h * 128 + e] = f2b(o[n][j] * rinv[j] * ng[e] * siluf_(g));
;       }
;     }
.LBB0_611:
	ds_read_u16 v4, v218 offset:1008
	v_mul_f32_e32 v5, v7, v30
	s_waitcnt lgkmcnt(0)
	v_lshlrev_b32_e32 v4, 16, v4
	v_mul_f32_e32 v5, v5, v225
	v_mul_f32_e32 v6, 0xbfb8aa3b, v4
	v_exp_f32_e32 v6, v6
	s_nop 0
	v_add_f32_e32 v6, 1.0, v6
	v_div_scale_f32 v7, s[50:51], v6, v6, v4
	v_rcp_f32_e32 v8, v7
	s_nop 0
	v_fma_f32 v9, -v7, v8, 1.0
	v_fmac_f32_e32 v8, v9, v8
	v_div_scale_f32 v9, vcc, v4, v6, v4
	v_mul_f32_e32 v10, v9, v8
	v_fma_f32 v11, -v7, v10, v9
	v_fmac_f32_e32 v10, v11, v8
	v_fma_f32 v7, -v7, v10, v9
	v_div_fmas_f32 v7, v7, v8, v10
	v_div_fixup_f32 v4, v7, v6, v4
	v_mul_f32_e32 v4, v5, v4
	v_bfe_u32 v5, v4, 16, 1
	v_add3_u32 v6, v4, v5, s39
	v_lshlrev_b64 v[4:5], 11, v[38:39]
	v_lshl_add_u64 v[4:5], v[32:33], 0, v[4:5]
	global_store_short_d16_hi v[4:5], v6, off offset:192
	s_or_b64 exec, exec, s[26:27]
	s_and_saveexec_b64 s[26:27], s[74:75]
	s_cbranch_execnz .LBB0_642

; DEVI float b2f(bfu b) { return __uint_as_float(((unsigned)b) << 16); }
; DEVI float siluf_(float x) { return x / (1.f + __expf(-x)); }
; DEVI void h3_item(const Params& P, int l, int ck, int h, char* smem, int tid) {
;     ...
;   bfu* UC = (bfu*)(P.ws + O_UC);
; #pragma unroll
;   for (int n = 0; n < 8; ++n)
; #pragma unroll
;     for (int j = 0; j < 4; ++j) {
;       int t = 16 * w + fq * 4 + j, e = n * 16 + fr;
;       if (t < L) {
;         float g = b2f(QT[t * 136 + e]);
;         UC[(long)(ci.lt0 + t) * 1024 + h * 128 + e] = f2b(o[n][j] * rinv[j] * ng[e] * siluf_(g));
;       }
;     }
.LBB0_613:
	ds_read_u16 v0, v218 offset:496
	v_mul_f32_e32 v1, v1, v43
	s_waitcnt lgkmcnt(0)
	v_lshlrev_b32_e32 v0, 16, v0
	v_mul_f32_e32 v1, v1, v226
	v_mul_f32_e32 v4, 0xbfb8aa3b, v0
	v_exp_f32_e32 v4, v4
	s_nop 0
	v_add_f32_e32 v4, 1.0, v4
	v_div_scale_f32 v5, s[50:51], v4, v4, v0
	v_rcp_f32_e32 v6, v5
	s_nop 0
	v_fma_f32 v7, -v5, v6, 1.0
	v_fmac_f32_e32 v6, v7, v6
	v_div_scale_f32 v7, vcc, v0, v4, v0
	v_mul_f32_e32 v8, v7, v6
	v_fma_f32 v9, -v5, v8, v7
	v_fmac_f32_e32 v8, v9, v6
	v_fma_f32 v5, -v5, v8, v7
	v_div_fmas_f32 v5, v5, v6, v8
	v_div_fixup_f32 v0, v5, v4, v0
	v_mul_f32_e32 v0, v1, v0
	v_bfe_u32 v1, v0, 16, 1
	v_add3_u32 v4, v0, v1, s39
	v_lshlrev_b64 v[0:1], 11, v[36:37]
	v_lshl_add_u64 v[0:1], v[32:33], 0, v[0:1]
	global_store_short_d16_hi v[0:1], v4, off offset:224
	s_or_b64 exec, exec, s[26:27]
	s_and_saveexec_b64 s[26:27], s[78:79]
	s_cbranch_execnz .LBB0_644

; DEVI float b2f(bfu b) { return __uint_as_float(((unsigned)b) << 16); }
; DEVI float siluf_(float x) { return x / (1.f + __expf(-x)); }
; DEVI void h3_item(const Params& P, int l, int ck, int h, char* smem, int tid) {
;     ...
;   bfu* UC = (bfu*)(P.ws + O_UC);
; #pragma unroll
;   for (int n = 0; n < 8; ++n)
; #pragma unroll
;     for (int j = 0; j < 4; ++j) {
;       int t = 16 * w + fq * 4 + j, e = n * 16 + fr;
;       if (t < L) {
;         float g = b2f(QT[t * 136 + e]);
;         UC[(long)(ci.lt0 + t) * 1024 + h * 128 + e] = f2b(o[n][j] * rinv[j] * ng[e] * siluf_(g));
;       }
;     }
.LBB0_615:
	ds_read_u16 v0, v218 offset:1040
	v_mul_f32_e32 v1, v3, v30
	s_waitcnt lgkmcnt(0)
	v_lshlrev_b32_e32 v0, 16, v0
	v_mul_f32_e32 v1, v1, v226
	v_mul_f32_e32 v2, 0xbfb8aa3b, v0
	v_exp_f32_e32 v2, v2
	s_nop 0
	v_add_f32_e32 v2, 1.0, v2
	v_div_scale_f32 v3, s[50:51], v2, v2, v0
	v_rcp_f32_e32 v4, v3
	s_nop 0
	v_fma_f32 v5, -v3, v4, 1.0
	v_fmac_f32_e32 v4, v5, v4
	v_div_scale_f32 v5, vcc, v0, v2, v0
	v_mul_f32_e32 v6, v5, v4
	v_fma_f32 v7, -v3, v6, v5
	v_fmac_f32_e32 v6, v7, v4
	v_fma_f32 v3, -v3, v6, v5
	v_div_fmas_f32 v3, v3, v4, v6
	v_div_fixup_f32 v0, v3, v2, v0
	v_mul_f32_e32 v0, v1, v0
	v_bfe_u32 v1, v0, 16, 1
	v_add3_u32 v2, v0, v1, s39
	v_lshlrev_b64 v[0:1], 11, v[38:39]
	v_lshl_add_u64 v[0:1], v[32:33], 0, v[0:1]
	global_store_short_d16_hi v[0:1], v2, off offset:224

; DEVI float b2f(bfu b) { return __uint_as_float(((unsigned)b) << 16); }
; DEVI float siluf_(float x) { return x / (1.f + __expf(-x)); }
; DEVI void h3_item(const Params& P, int l, int ck, int h, char* smem, int tid) {
;     ...
;   bfu* UC = (bfu*)(P.ws + O_UC);
; #pragma unroll
;   for (int n = 0; n < 8; ++n)
; #pragma unroll
;     for (int j = 0; j < 4; ++j) {
;       int t = 16 * w + fq * 4 + j, e = n * 16 + fr;
;       if (t < L) {
;         float g = b2f(QT[t * 136 + e]);
;         UC[(long)(ci.lt0 + t) * 1024 + h * 128 + e] = f2b(o[n][j] * rinv[j] * ng[e] * siluf_(g));
;       }
;     }
.LBB0_618:
	ds_read_u16 v31, v218 offset:32
	v_mul_f32_e32 v24, v24, v42
	s_waitcnt lgkmcnt(0)
	v_lshlrev_b32_e32 v31, 16, v31
	v_mul_f32_e32 v24, v24, v220
	v_mul_f32_e32 v41, 0xbfb8aa3b, v31
	v_exp_f32_e32 v41, v41
	s_nop 0
	v_add_f32_e32 v41, 1.0, v41
	v_div_scale_f32 v44, s[50:51], v41, v41, v31
	v_rcp_f32_e32 v45, v44
	s_nop 0
	v_fma_f32 v46, -v44, v45, 1.0
	v_fmac_f32_e32 v45, v46, v45
	v_div_scale_f32 v46, vcc, v31, v41, v31
	v_mul_f32_e32 v47, v46, v45
	v_fma_f32 v48, -v44, v47, v46
	v_fmac_f32_e32 v47, v48, v45
	v_fma_f32 v44, -v44, v47, v46
	v_div_fmas_f32 v44, v44, v45, v47
	v_div_fixup_f32 v31, v44, v41, v31
	v_mul_f32_e32 v24, v24, v31
	v_bfe_u32 v31, v24, 16, 1
	v_lshlrev_b64 v[44:45], 11, v[34:35]
	v_add3_u32 v24, v24, v31, s39
	v_lshl_add_u64 v[44:45], v[32:33], 0, v[44:45]
	global_store_short_d16_hi v[44:45], v24, off offset:32
	s_or_b64 exec, exec, s[26:27]
	s_and_saveexec_b64 s[26:27], s[76:77]
	s_cbranch_execnz .LBB0_589

; DEVI float b2f(bfu b) { return __uint_as_float(((unsigned)b) << 16); }
; DEVI float siluf_(float x) { return x / (1.f + __expf(-x)); }
; DEVI void h3_item(const Params& P, int l, int ck, int h, char* smem, int tid) {
;     ...
;   bfu* UC = (bfu*)(P.ws + O_UC);
; #pragma unroll
;   for (int n = 0; n < 8; ++n)
; #pragma unroll
;     for (int j = 0; j < 4; ++j) {
;       int t = 16 * w + fq * 4 + j, e = n * 16 + fr;
;       if (t < L) {
;         float g = b2f(QT[t * 136 + e]);
;         UC[(long)(ci.lt0 + t) * 1024 + h * 128 + e] = f2b(o[n][j] * rinv[j] * ng[e] * siluf_(g));
;       }
;     }
.LBB0_620:
	v_mul_f32_e32 v25, v26, v40
	ds_read_u16 v24, v218 offset:576
	s_waitcnt lgkmcnt(0)
	v_lshlrev_b32_e32 v24, 16, v24
	v_mul_f32_e32 v25, v25, v220
	v_mul_f32_e32 v26, 0xbfb8aa3b, v24
	v_exp_f32_e32 v26, v26
	s_nop 0
	v_add_f32_e32 v26, 1.0, v26
	v_div_scale_f32 v31, s[50:51], v26, v26, v24
	v_rcp_f32_e32 v41, v31
	s_nop 0
	v_fma_f32 v44, -v31, v41, 1.0
	v_fmac_f32_e32 v41, v44, v41
	v_div_scale_f32 v44, vcc, v24, v26, v24
	v_mul_f32_e32 v45, v44, v41
	v_fma_f32 v46, -v31, v45, v44
	v_fmac_f32_e32 v45, v46, v41
	v_fma_f32 v31, -v31, v45, v44
	v_div_fmas_f32 v31, v31, v41, v45
	v_div_fixup_f32 v24, v31, v26, v24
	v_mul_f32_e32 v24, v25, v24
	v_bfe_u32 v25, v24, 16, 1
	v_add3_u32 v26, v24, v25, s39
	v_lshlrev_b64 v[24:25], 11, v[28:29]
	v_lshl_add_u64 v[24:25], v[32:33], 0, v[24:25]
	global_store_short_d16_hi v[24:25], v26, off offset:32
	s_or_b64 exec, exec, s[26:27]
	s_and_saveexec_b64 s[26:27], s[80:81]
	s_cbranch_execnz .LBB0_591

; DEVI float b2f(bfu b) { return __uint_as_float(((unsigned)b) << 16); }
; DEVI float siluf_(float x) { return x / (1.f + __expf(-x)); }
; DEVI void h3_item(const Params& P, int l, int ck, int h, char* smem, int tid) {
;     ...
;   bfu* UC = (bfu*)(P.ws + O_UC);
; #pragma unroll
;   for (int n = 0; n < 8; ++n)
; #pragma unroll
;     for (int j = 0; j < 4; ++j) {
;       int t = 16 * w + fq * 4 + j, e = n * 16 + fr;
;       if (t < L) {
;         float g = b2f(QT[t * 136 + e]);
;         UC[(long)(ci.lt0 + t) * 1024 + h * 128 + e] = f2b(o[n][j] * rinv[j] * ng[e] * siluf_(g));
;       }
;     }
.LBB0_622:
	ds_read_u16 v24, v218 offset:64
	v_mul_f32_e32 v20, v20, v42
	s_waitcnt lgkmcnt(0)
	v_lshlrev_b32_e32 v24, 16, v24
	v_mul_f32_e32 v20, v20, v221
	v_mul_f32_e32 v25, 0xbfb8aa3b, v24
	v_exp_f32_e32 v25, v25
	s_nop 0
	v_add_f32_e32 v25, 1.0, v25
	v_div_scale_f32 v26, s[50:51], v25, v25, v24
	v_rcp_f32_e32 v27, v26
	s_nop 0
	v_fma_f32 v31, -v26, v27, 1.0
	v_fmac_f32_e32 v27, v31, v27
	v_div_scale_f32 v31, vcc, v24, v25, v24
	v_mul_f32_e32 v41, v31, v27
	v_fma_f32 v44, -v26, v41, v31
	v_fmac_f32_e32 v41, v44, v27
	v_fma_f32 v26, -v26, v41, v31
	v_div_fmas_f32 v26, v26, v27, v41
	v_div_fixup_f32 v24, v26, v25, v24
	v_mul_f32_e32 v20, v20, v24
	v_bfe_u32 v24, v20, 16, 1
	v_add3_u32 v20, v20, v24, s39
	v_lshlrev_b64 v[24:25], 11, v[34:35]
	v_lshl_add_u64 v[24:25], v[32:33], 0, v[24:25]
	global_store_short_d16_hi v[24:25], v20, off offset:64
	s_or_b64 exec, exec, s[26:27]
	s_and_saveexec_b64 s[26:27], s[76:77]
	s_cbranch_execnz .LBB0_593

; DEVI float b2f(bfu b) { return __uint_as_float(((unsigned)b) << 16); }
; DEVI float siluf_(float x) { return x / (1.f + __expf(-x)); }
; DEVI void h3_item(const Params& P, int l, int ck, int h, char* smem, int tid) {
;     ...
;   bfu* UC = (bfu*)(P.ws + O_UC);
; #pragma unroll
;   for (int n = 0; n < 8; ++n)
; #pragma unroll
;     for (int j = 0; j < 4; ++j) {
;       int t = 16 * w + fq * 4 + j, e = n * 16 + fr;
;       if (t < L) {
;         float g = b2f(QT[t * 136 + e]);
;         UC[(long)(ci.lt0 + t) * 1024 + h * 128 + e] = f2b(o[n][j] * rinv[j] * ng[e] * siluf_(g));
;       }
;     }
.LBB0_624:
	v_mul_f32_e32 v21, v22, v40
	ds_read_u16 v20, v218 offset:608
	s_waitcnt lgkmcnt(0)
	v_lshlrev_b32_e32 v20, 16, v20
	v_mul_f32_e32 v21, v21, v221
	v_mul_f32_e32 v22, 0xbfb8aa3b, v20
	v_exp_f32_e32 v22, v22
	s_nop 0
	v_add_f32_e32 v22, 1.0, v22
	v_div_scale_f32 v24, s[50:51], v22, v22, v20
	v_rcp_f32_e32 v25, v24
	s_nop 0
	v_fma_f32 v26, -v24, v25, 1.0
	v_fmac_f32_e32 v25, v26, v25
	v_div_scale_f32 v26, vcc, v20, v22, v20
	v_mul_f32_e32 v27, v26, v25
	v_fma_f32 v31, -v24, v27, v26
	v_fmac_f32_e32 v27, v31, v25
	v_fma_f32 v24, -v24, v27, v26
	v_div_fmas_f32 v24, v24, v25, v27
	v_div_fixup_f32 v20, v24, v22, v20
	v_mul_f32_e32 v20, v21, v20
	v_bfe_u32 v21, v20, 16, 1
	v_add3_u32 v22, v20, v21, s39
	v_lshlrev_b64 v[20:21], 11, v[28:29]
	v_lshl_add_u64 v[20:21], v[32:33], 0, v[20:21]
	global_store_short_d16_hi v[20:21], v22, off offset:64
	s_or_b64 exec, exec, s[26:27]
	s_and_saveexec_b64 s[26:27], s[80:81]
	s_cbranch_execnz .LBB0_595

; DEVI float b2f(bfu b) { return __uint_as_float(((unsigned)b) << 16); }
; DEVI float siluf_(float x) { return x / (1.f + __expf(-x)); }
; DEVI void h3_item(const Params& P, int l, int ck, int h, char* smem, int tid) {
;     ...
;   bfu* UC = (bfu*)(P.ws + O_UC);
; #pragma unroll
;   for (int n = 0; n < 8; ++n)
; #pragma unroll
;     for (int j = 0; j < 4; ++j) {
;       int t = 16 * w + fq * 4 + j, e = n * 16 + fr;
;       if (t < L) {
;         float g = b2f(QT[t * 136 + e]);
;         UC[(long)(ci.lt0 + t) * 1024 + h * 128 + e] = f2b(o[n][j] * rinv[j] * ng[e] * siluf_(g));
;       }
;     }
.LBB0_626:
	ds_read_u16 v20, v218 offset:96
	v_mul_f32_e32 v16, v16, v42
	s_waitcnt lgkmcnt(0)
	v_lshlrev_b32_e32 v20, 16, v20
	v_mul_f32_e32 v16, v16, v222
	v_mul_f32_e32 v21, 0xbfb8aa3b, v20
	v_exp_f32_e32 v21, v21
	s_nop 0
	v_add_f32_e32 v21, 1.0, v21
	v_div_scale_f32 v22, s[50:51], v21, v21, v20
	v_rcp_f32_e32 v23, v22
	s_nop 0
	v_fma_f32 v24, -v22, v23, 1.0
	v_fmac_f32_e32 v23, v24, v23
	v_div_scale_f32 v24, vcc, v20, v21, v20
	v_mul_f32_e32 v25, v24, v23
	v_fma_f32 v26, -v22, v25, v24
	v_fmac_f32_e32 v25, v26, v23
	v_fma_f32 v22, -v22, v25, v24
	v_div_fmas_f32 v22, v22, v23, v25
	v_div_fixup_f32 v20, v22, v21, v20
	v_mul_f32_e32 v16, v16, v20
	v_bfe_u32 v20, v16, 16, 1
	v_add3_u32 v16, v16, v20, s39
	v_lshlrev_b64 v[20:21], 11, v[34:35]
	v_lshl_add_u64 v[20:21], v[32:33], 0, v[20:21]
	global_store_short_d16_hi v[20:21], v16, off offset:96
	s_or_b64 exec, exec, s[26:27]
	s_and_saveexec_b64 s[26:27], s[76:77]
	s_cbranch_execnz .LBB0_597

; DEVI float b2f(bfu b) { return __uint_as_float(((unsigned)b) << 16); }
; DEVI float siluf_(float x) { return x / (1.f + __expf(-x)); }
; DEVI void h3_item(const Params& P, int l, int ck, int h, char* smem, int tid) {
;     ...
;   bfu* UC = (bfu*)(P.ws + O_UC);
; #pragma unroll
;   for (int n = 0; n < 8; ++n)
; #pragma unroll
;     for (int j = 0; j < 4; ++j) {
;       int t = 16 * w + fq * 4 + j, e = n * 16 + fr;
;       if (t < L) {
;         float g = b2f(QT[t * 136 + e]);
;         UC[(long)(ci.lt0 + t) * 1024 + h * 128 + e] = f2b(o[n][j] * rinv[j] * ng[e] * siluf_(g));
;       }
;     }
.LBB0_628:
	v_mul_f32_e32 v17, v18, v40
	ds_read_u16 v16, v218 offset:640
	s_waitcnt lgkmcnt(0)
	v_lshlrev_b32_e32 v16, 16, v16
	v_mul_f32_e32 v17, v17, v222
	v_mul_f32_e32 v18, 0xbfb8aa3b, v16
	v_exp_f32_e32 v18, v18
	s_nop 0
	v_add_f32_e32 v18, 1.0, v18
	v_div_scale_f32 v20, s[50:51], v18, v18, v16
	v_rcp_f32_e32 v21, v20
	s_nop 0
	v_fma_f32 v22, -v20, v21, 1.0
	v_fmac_f32_e32 v21, v22, v21
	v_div_scale_f32 v22, vcc, v16, v18, v16
	v_mul_f32_e32 v23, v22, v21
	v_fma_f32 v24, -v20, v23, v22
	v_fmac_f32_e32 v23, v24, v21
	v_fma_f32 v20, -v20, v23, v22
	v_div_fmas_f32 v20, v20, v21, v23
	v_div_fixup_f32 v16, v20, v18, v16
	v_mul_f32_e32 v16, v17, v16
	v_bfe_u32 v17, v16, 16, 1
	v_add3_u32 v18, v16, v17, s39
	v_lshlrev_b64 v[16:17], 11, v[28:29]
	v_lshl_add_u64 v[16:17], v[32:33], 0, v[16:17]
	global_store_short_d16_hi v[16:17], v18, off offset:96
	s_or_b64 exec, exec, s[26:27]
	s_and_saveexec_b64 s[26:27], s[80:81]
	s_cbranch_execnz .LBB0_599

; DEVI float b2f(bfu b) { return __uint_as_float(((unsigned)b) << 16); }
; DEVI float siluf_(float x) { return x / (1.f + __expf(-x)); }
; DEVI void h3_item(const Params& P, int l, int ck, int h, char* smem, int tid) {
;     ...
;   bfu* UC = (bfu*)(P.ws + O_UC);
; #pragma unroll
;   for (int n = 0; n < 8; ++n)
; #pragma unroll
;     for (int j = 0; j < 4; ++j) {
;       int t = 16 * w + fq * 4 + j, e = n * 16 + fr;
;       if (t < L) {
;         float g = b2f(QT[t * 136 + e]);
;         UC[(long)(ci.lt0 + t) * 1024 + h * 128 + e] = f2b(o[n][j] * rinv[j] * ng[e] * siluf_(g));
;       }
;     }
.LBB0_630:
	ds_read_u16 v16, v218 offset:128
	v_mul_f32_e32 v12, v12, v42
	s_waitcnt lgkmcnt(0)
	v_lshlrev_b32_e32 v16, 16, v16
	v_mul_f32_e32 v12, v12, v223
	v_mul_f32_e32 v17, 0xbfb8aa3b, v16
	v_exp_f32_e32 v17, v17
	s_nop 0
	v_add_f32_e32 v17, 1.0, v17
	v_div_scale_f32 v18, s[50:51], v17, v17, v16
	v_rcp_f32_e32 v19, v18
	s_nop 0
	v_fma_f32 v20, -v18, v19, 1.0
	v_fmac_f32_e32 v19, v20, v19
	v_div_scale_f32 v20, vcc, v16, v17, v16
	v_mul_f32_e32 v21, v20, v19
	v_fma_f32 v22, -v18, v21, v20
	v_fmac_f32_e32 v21, v22, v19
	v_fma_f32 v18, -v18, v21, v20
	v_div_fmas_f32 v18, v18, v19, v21
	v_div_fixup_f32 v16, v18, v17, v16
	v_mul_f32_e32 v12, v12, v16
	v_bfe_u32 v16, v12, 16, 1
	v_add3_u32 v12, v12, v16, s39
	v_lshlrev_b64 v[16:17], 11, v[34:35]
	v_lshl_add_u64 v[16:17], v[32:33], 0, v[16:17]
	global_store_short_d16_hi v[16:17], v12, off offset:128
	s_or_b64 exec, exec, s[26:27]
	s_and_saveexec_b64 s[26:27], s[76:77]
	s_cbranch_execnz .LBB0_601

; DEVI float b2f(bfu b) { return __uint_as_float(((unsigned)b) << 16); }
; DEVI float siluf_(float x) { return x / (1.f + __expf(-x)); }
; DEVI void h3_item(const Params& P, int l, int ck, int h, char* smem, int tid) {
;     ...
;   bfu* UC = (bfu*)(P.ws + O_UC);
; #pragma unroll
;   for (int n = 0; n < 8; ++n)
; #pragma unroll
;     for (int j = 0; j < 4; ++j) {
;       int t = 16 * w + fq * 4 + j, e = n * 16 + fr;
;       if (t < L) {
;         float g = b2f(QT[t * 136 + e]);
;         UC[(long)(ci.lt0 + t) * 1024 + h * 128 + e] = f2b(o[n][j] * rinv[j] * ng[e] * siluf_(g));
;       }
;     }
.LBB0_632:
	v_mul_f32_e32 v13, v14, v40
	ds_read_u16 v12, v218 offset:672
	s_waitcnt lgkmcnt(0)
	v_lshlrev_b32_e32 v12, 16, v12
	v_mul_f32_e32 v13, v13, v223
	v_mul_f32_e32 v14, 0xbfb8aa3b, v12
	v_exp_f32_e32 v14, v14
	s_nop 0
	v_add_f32_e32 v14, 1.0, v14
	v_div_scale_f32 v16, s[50:51], v14, v14, v12
	v_rcp_f32_e32 v17, v16
	s_nop 0
	v_fma_f32 v18, -v16, v17, 1.0
	v_fmac_f32_e32 v17, v18, v17
	v_div_scale_f32 v18, vcc, v12, v14, v12
	v_mul_f32_e32 v19, v18, v17
	v_fma_f32 v20, -v16, v19, v18
	v_fmac_f32_e32 v19, v20, v17
	v_fma_f32 v16, -v16, v19, v18
	v_div_fmas_f32 v16, v16, v17, v19
	v_div_fixup_f32 v12, v16, v14, v12
	v_mul_f32_e32 v12, v13, v12
	v_bfe_u32 v13, v12, 16, 1
	v_add3_u32 v14, v12, v13, s39
	v_lshlrev_b64 v[12:13], 11, v[28:29]
	v_lshl_add_u64 v[12:13], v[32:33], 0, v[12:13]
	global_store_short_d16_hi v[12:13], v14, off offset:128
	s_or_b64 exec, exec, s[26:27]
	s_and_saveexec_b64 s[26:27], s[80:81]
	s_cbranch_execnz .LBB0_603

; DEVI float b2f(bfu b) { return __uint_as_float(((unsigned)b) << 16); }
; DEVI float siluf_(float x) { return x / (1.f + __expf(-x)); }
; DEVI void h3_item(const Params& P, int l, int ck, int h, char* smem, int tid) {
;     ...
;   bfu* UC = (bfu*)(P.ws + O_UC);
; #pragma unroll
;   for (int n = 0; n < 8; ++n)
; #pragma unroll
;     for (int j = 0; j < 4; ++j) {
;       int t = 16 * w + fq * 4 + j, e = n * 16 + fr;
;       if (t < L) {
;         float g = b2f(QT[t * 136 + e]);
;         UC[(long)(ci.lt0 + t) * 1024 + h * 128 + e] = f2b(o[n][j] * rinv[j] * ng[e] * siluf_(g));
;       }
;     }
.LBB0_634:
	ds_read_u16 v12, v218 offset:160
	v_mul_f32_e32 v8, v8, v42
	s_waitcnt lgkmcnt(0)
	v_lshlrev_b32_e32 v12, 16, v12
	v_mul_f32_e32 v8, v8, v224
	v_mul_f32_e32 v13, 0xbfb8aa3b, v12
	v_exp_f32_e32 v13, v13
	s_nop 0
	v_add_f32_e32 v13, 1.0, v13
	v_div_scale_f32 v14, s[50:51], v13, v13, v12
	v_rcp_f32_e32 v15, v14
	s_nop 0
	v_fma_f32 v16, -v14, v15, 1.0
	v_fmac_f32_e32 v15, v16, v15
	v_div_scale_f32 v16, vcc, v12, v13, v12
	v_mul_f32_e32 v17, v16, v15
	v_fma_f32 v18, -v14, v17, v16
	v_fmac_f32_e32 v17, v18, v15
	v_fma_f32 v14, -v14, v17, v16
	v_div_fmas_f32 v14, v14, v15, v17
	v_div_fixup_f32 v12, v14, v13, v12
	v_mul_f32_e32 v8, v8, v12
	v_bfe_u32 v12, v8, 16, 1
	v_add3_u32 v8, v8, v12, s39
	v_lshlrev_b64 v[12:13], 11, v[34:35]
	v_lshl_add_u64 v[12:13], v[32:33], 0, v[12:13]
	global_store_short_d16_hi v[12:13], v8, off offset:160
	s_or_b64 exec, exec, s[26:27]
	s_and_saveexec_b64 s[26:27], s[76:77]
	s_cbranch_execnz .LBB0_605

; DEVI float b2f(bfu b) { return __uint_as_float(((unsigned)b) << 16); }
; DEVI float siluf_(float x) { return x / (1.f + __expf(-x)); }
; DEVI void h3_item(const Params& P, int l, int ck, int h, char* smem, int tid) {
;     ...
;   bfu* UC = (bfu*)(P.ws + O_UC);
; #pragma unroll
;   for (int n = 0; n < 8; ++n)
; #pragma unroll
;     for (int j = 0; j < 4; ++j) {
;       int t = 16 * w + fq * 4 + j, e = n * 16 + fr;
;       if (t < L) {
;         float g = b2f(QT[t * 136 + e]);
;         UC[(long)(ci.lt0 + t) * 1024 + h * 128 + e] = f2b(o[n][j] * rinv[j] * ng[e] * siluf_(g));
;       }
;     }
.LBB0_636:
	v_mul_f32_e32 v9, v10, v40
	ds_read_u16 v8, v218 offset:704
	s_waitcnt lgkmcnt(0)
	v_lshlrev_b32_e32 v8, 16, v8
	v_mul_f32_e32 v9, v9, v224
	v_mul_f32_e32 v10, 0xbfb8aa3b, v8
	v_exp_f32_e32 v10, v10
	s_nop 0
	v_add_f32_e32 v10, 1.0, v10
	v_div_scale_f32 v12, s[50:51], v10, v10, v8
	v_rcp_f32_e32 v13, v12
	s_nop 0
	v_fma_f32 v14, -v12, v13, 1.0
	v_fmac_f32_e32 v13, v14, v13
	v_div_scale_f32 v14, vcc, v8, v10, v8
	v_mul_f32_e32 v15, v14, v13
	v_fma_f32 v16, -v12, v15, v14
	v_fmac_f32_e32 v15, v16, v13
	v_fma_f32 v12, -v12, v15, v14
	v_div_fmas_f32 v12, v12, v13, v15
	v_div_fixup_f32 v8, v12, v10, v8
	v_mul_f32_e32 v8, v9, v8
	v_bfe_u32 v9, v8, 16, 1
	v_add3_u32 v10, v8, v9, s39
	v_lshlrev_b64 v[8:9], 11, v[28:29]
	v_lshl_add_u64 v[8:9], v[32:33], 0, v[8:9]
	global_store_short_d16_hi v[8:9], v10, off offset:160
	s_or_b64 exec, exec, s[26:27]
	s_and_saveexec_b64 s[26:27], s[80:81]
	s_cbranch_execnz .LBB0_607

; DEVI float b2f(bfu b) { return __uint_as_float(((unsigned)b) << 16); }
; DEVI float siluf_(float x) { return x / (1.f + __expf(-x)); }
; DEVI void h3_item(const Params& P, int l, int ck, int h, char* smem, int tid) {
;     ...
;   bfu* UC = (bfu*)(P.ws + O_UC);
; #pragma unroll
;   for (int n = 0; n < 8; ++n)
; #pragma unroll
;     for (int j = 0; j < 4; ++j) {
;       int t = 16 * w + fq * 4 + j, e = n * 16 + fr;
;       if (t < L) {
;         float g = b2f(QT[t * 136 + e]);
;         UC[(long)(ci.lt0 + t) * 1024 + h * 128 + e] = f2b(o[n][j] * rinv[j] * ng[e] * siluf_(g));
;       }
;     }
.LBB0_638:
	ds_read_u16 v8, v218 offset:192
	v_mul_f32_e32 v4, v4, v42
	s_waitcnt lgkmcnt(0)
	v_lshlrev_b32_e32 v8, 16, v8
	v_mul_f32_e32 v4, v4, v225
	v_mul_f32_e32 v9, 0xbfb8aa3b, v8
	v_exp_f32_e32 v9, v9
	s_nop 0
	v_add_f32_e32 v9, 1.0, v9
	v_div_scale_f32 v10, s[50:51], v9, v9, v8
	v_rcp_f32_e32 v11, v10
	s_nop 0
	v_fma_f32 v12, -v10, v11, 1.0
	v_fmac_f32_e32 v11, v12, v11
	v_div_scale_f32 v12, vcc, v8, v9, v8
	v_mul_f32_e32 v13, v12, v11
	v_fma_f32 v14, -v10, v13, v12
	v_fmac_f32_e32 v13, v14, v11
	v_fma_f32 v10, -v10, v13, v12
	v_div_fmas_f32 v10, v10, v11, v13
	v_div_fixup_f32 v8, v10, v9, v8
	v_mul_f32_e32 v4, v4, v8
	v_bfe_u32 v8, v4, 16, 1
	v_add3_u32 v4, v4, v8, s39
	v_lshlrev_b64 v[8:9], 11, v[34:35]
	v_lshl_add_u64 v[8:9], v[32:33], 0, v[8:9]
	global_store_short_d16_hi v[8:9], v4, off offset:192
	s_or_b64 exec, exec, s[26:27]
	s_and_saveexec_b64 s[26:27], s[76:77]
	s_cbranch_execnz .LBB0_609

; DEVI float b2f(bfu b) { return __uint_as_float(((unsigned)b) << 16); }
; DEVI float siluf_(float x) { return x / (1.f + __expf(-x)); }
; DEVI void h3_item(const Params& P, int l, int ck, int h, char* smem, int tid) {
;     ...
;   bfu* UC = (bfu*)(P.ws + O_UC);
; #pragma unroll
;   for (int n = 0; n < 8; ++n)
; #pragma unroll
;     for (int j = 0; j < 4; ++j) {
;       int t = 16 * w + fq * 4 + j, e = n * 16 + fr;
;       if (t < L) {
;         float g = b2f(QT[t * 136 + e]);
;         UC[(long)(ci.lt0 + t) * 1024 + h * 128 + e] = f2b(o[n][j] * rinv[j] * ng[e] * siluf_(g));
;       }
;     }
.LBB0_640:
	v_mul_f32_e32 v5, v6, v40
	ds_read_u16 v4, v218 offset:736
	s_waitcnt lgkmcnt(0)
	v_lshlrev_b32_e32 v4, 16, v4
	v_mul_f32_e32 v5, v5, v225
	v_mul_f32_e32 v6, 0xbfb8aa3b, v4
	v_exp_f32_e32 v6, v6
	s_nop 0
	v_add_f32_e32 v6, 1.0, v6
	v_div_scale_f32 v8, s[50:51], v6, v6, v4
	v_rcp_f32_e32 v9, v8
	s_nop 0
	v_fma_f32 v10, -v8, v9, 1.0
	v_fmac_f32_e32 v9, v10, v9
	v_div_scale_f32 v10, vcc, v4, v6, v4
	v_mul_f32_e32 v11, v10, v9
	v_fma_f32 v12, -v8, v11, v10
	v_fmac_f32_e32 v11, v12, v9
	v_fma_f32 v8, -v8, v11, v10
	v_div_fmas_f32 v8, v8, v9, v11
	v_div_fixup_f32 v4, v8, v6, v4
	v_mul_f32_e32 v4, v5, v4
	v_bfe_u32 v5, v4, 16, 1
	v_add3_u32 v6, v4, v5, s39
	v_lshlrev_b64 v[4:5], 11, v[28:29]
	v_lshl_add_u64 v[4:5], v[32:33], 0, v[4:5]
	global_store_short_d16_hi v[4:5], v6, off offset:192
	s_or_b64 exec, exec, s[26:27]
	s_and_saveexec_b64 s[26:27], s[80:81]
	s_cbranch_execnz .LBB0_611

; DEVI float b2f(bfu b) { return __uint_as_float(((unsigned)b) << 16); }
; DEVI float siluf_(float x) { return x / (1.f + __expf(-x)); }
; DEVI void h3_item(const Params& P, int l, int ck, int h, char* smem, int tid) {
;     ...
;   bfu* UC = (bfu*)(P.ws + O_UC);
; #pragma unroll
;   for (int n = 0; n < 8; ++n)
; #pragma unroll
;     for (int j = 0; j < 4; ++j) {
;       int t = 16 * w + fq * 4 + j, e = n * 16 + fr;
;       if (t < L) {
;         float g = b2f(QT[t * 136 + e]);
;         UC[(long)(ci.lt0 + t) * 1024 + h * 128 + e] = f2b(o[n][j] * rinv[j] * ng[e] * siluf_(g));
;       }
;     }
.LBB0_642:
	ds_read_u16 v4, v218 offset:224
	v_mul_f32_e32 v0, v0, v42
	s_waitcnt lgkmcnt(0)
	v_lshlrev_b32_e32 v4, 16, v4
	v_mul_f32_e32 v0, v0, v226
	v_mul_f32_e32 v5, 0xbfb8aa3b, v4
	v_exp_f32_e32 v5, v5
	s_nop 0
	v_add_f32_e32 v5, 1.0, v5
	v_div_scale_f32 v6, s[50:51], v5, v5, v4
	v_rcp_f32_e32 v7, v6
	s_nop 0
	v_fma_f32 v8, -v6, v7, 1.0
	v_fmac_f32_e32 v7, v8, v7
	v_div_scale_f32 v8, vcc, v4, v5, v4
	v_mul_f32_e32 v9, v8, v7
	v_fma_f32 v10, -v6, v9, v8
	v_fmac_f32_e32 v9, v10, v7
	v_fma_f32 v6, -v6, v9, v8
	v_div_fmas_f32 v6, v6, v7, v9
	v_div_fixup_f32 v4, v6, v5, v4
	v_mul_f32_e32 v0, v0, v4
	v_bfe_u32 v4, v0, 16, 1
	v_add3_u32 v0, v0, v4, s39
	v_lshlrev_b64 v[4:5], 11, v[34:35]
	v_lshl_add_u64 v[4:5], v[32:33], 0, v[4:5]
	global_store_short_d16_hi v[4:5], v0, off offset:224
	s_or_b64 exec, exec, s[26:27]
	s_and_saveexec_b64 s[26:27], s[76:77]
	s_cbranch_execnz .LBB0_613

; DEVI float b2f(bfu b) { return __uint_as_float(((unsigned)b) << 16); }
; DEVI float siluf_(float x) { return x / (1.f + __expf(-x)); }
; DEVI void h3_item(const Params& P, int l, int ck, int h, char* smem, int tid) {
;     ...
;   bfu* UC = (bfu*)(P.ws + O_UC);
; #pragma unroll
;   for (int n = 0; n < 8; ++n)
; #pragma unroll
;     for (int j = 0; j < 4; ++j) {
;       int t = 16 * w + fq * 4 + j, e = n * 16 + fr;
;       if (t < L) {
;         float g = b2f(QT[t * 136 + e]);
;         UC[(long)(ci.lt0 + t) * 1024 + h * 128 + e] = f2b(o[n][j] * rinv[j] * ng[e] * siluf_(g));
;       }
;     }
.LBB0_644:
	v_mul_f32_e32 v1, v2, v40
	ds_read_u16 v0, v218 offset:768
	s_waitcnt lgkmcnt(0)
	v_lshlrev_b32_e32 v0, 16, v0
	v_mul_f32_e32 v1, v1, v226
	v_mul_f32_e32 v2, 0xbfb8aa3b, v0
	v_exp_f32_e32 v2, v2
	s_nop 0
	v_add_f32_e32 v2, 1.0, v2
	v_div_scale_f32 v4, s[50:51], v2, v2, v0
	v_rcp_f32_e32 v5, v4
	s_nop 0
	v_fma_f32 v6, -v4, v5, 1.0
	v_fmac_f32_e32 v5, v6, v5
	v_div_scale_f32 v6, vcc, v0, v2, v0
	v_mul_f32_e32 v7, v6, v5
	v_fma_f32 v8, -v4, v7, v6
	v_fmac_f32_e32 v7, v8, v5
	v_fma_f32 v4, -v4, v7, v6
	v_div_fmas_f32 v4, v4, v5, v7
	v_div_fixup_f32 v0, v4, v2, v0
	v_mul_f32_e32 v0, v1, v0
	v_bfe_u32 v1, v0, 16, 1
	v_add3_u32 v2, v0, v1, s39
	v_lshlrev_b64 v[0:1], 11, v[28:29]
	v_lshl_add_u64 v[0:1], v[32:33], 0, v[0:1]
	global_store_short_d16_hi v[0:1], v2, off offset:224
	s_or_b64 exec, exec, s[26:27]
	s_and_saveexec_b64 s[26:27], s[80:81]
	s_cbranch_execnz .LBB0_615
	s_branch .LBB0_616
